# P0 mods partial GEMV: 32 k per batch with 56 loads in flight (was 64 serialized 2-k round trips), same op order
# speedup vs baseline: 1.0054x; 1.0040x over previous
; __device__ __forceinline__ float fsilu(float x) { return x * fsig(x); }
; __global__ void __launch_bounds__(512, 2) fwd_megakernel(Params Parg) {
;     ...
;                 r -= NCONV; const int kc = r / 144, nc = r % 144, n = nc * 64 + lane;
;                 float a0 = 0.f, a1 = 0.f, a2 = 0.f;
;                 for (int k = kc * 128; k < kc * 128 + 128; ++k) { const float w = __builtin_nontemporal_load(&w_mod[(size_t)k * (NMOD * D) + n]); a0 += fsilu(cvec[k]) * w; a1 += fsilu(cvec[D + k]) * w; a2 += fsilu(cctx[k]) * w; }
;                 part[(kc * 3 + 0) * (NMOD * D) + n] = a0; part[(kc * 3 + 1) * (NMOD * D) + n] = a1; part[(kc * 3 + 2) * (NMOD * D) + n] = a2;
.LBB0_146:
	s_andn2_b64 vcc, exec, s[6:7]
	s_cbranch_vccnz .LBB0_7
	s_and_b32 s6, 0xffff, s4
	s_mul_hi_u32 s6, s6, 0x1c71c72
	s_lshl_b32 s30, s6, 7
	s_add_i32 s6, s3, 0xc300
	s_and_b32 s7, s6, 0xffff
	s_mul_i32 s24, s7, 0xe38f
	s_lshr_b32 s24, s24, 23
	s_mul_i32 s31, s24, 0x90
	s_sub_i32 s6, s6, s31
	s_lshl_b32 s6, s6, 6
	s_and_b32 s6, s6, 0xffc0
	s_mul_hi_u32 s35, s7, 0x1c71c72
	v_or_b32_e32 v28, s6, v1
	s_lshl_b32 s31, s24, 7
	s_mul_i32 s6, s35, 0x480000
	s_add_u32 s6, s10, s6
	v_lshlrev_b32_e32 v8, 2, v28
	s_addc_u32 s7, s11, 0
	v_lshl_add_u64 v[2:3], s[6:7], 0, v[8:9]
	s_sub_i32 s6, s30, s31
	v_mov_b32_e32 v29, 0
	s_add_i32 s34, s6, 0x80
	s_lshl_b32 s35, s35, 9
	s_mov_b64 s[6:7], s[8:9]
	s_mov_b64 s[30:31], s[20:21]
	v_mov_b32_e32 v4, 0
	v_mov_b32_e32 v5, v29
	s_add_u32 s56, s30, s35
	s_addc_u32 s57, s31, 0
	s_add_u32 s58, s6, s35
	s_addc_u32 s59, s7, 0
	s_mov_b32 s60, 0x9000
	s_mov_b32 s61, 0
	s_mov_b32 s62, 4
.Lmods_batch:
	global_load_dwordx4 v[80:83], v9, s[56:57]
	global_load_dwordx4 v[84:87], v9, s[56:57] offset:16
	global_load_dwordx4 v[88:91], v9, s[56:57] offset:32
	global_load_dwordx4 v[92:95], v9, s[56:57] offset:48
	global_load_dwordx4 v[96:99], v9, s[56:57] offset:64
	global_load_dwordx4 v[100:103], v9, s[56:57] offset:80
	global_load_dwordx4 v[104:107], v9, s[56:57] offset:96
	global_load_dwordx4 v[108:111], v9, s[56:57] offset:112
	global_load_dwordx4 v[112:115], v53, s[56:57]
	global_load_dwordx4 v[116:119], v53, s[56:57] offset:16
	global_load_dwordx4 v[120:123], v53, s[56:57] offset:32
	global_load_dwordx4 v[124:127], v53, s[56:57] offset:48
	global_load_dwordx4 v[128:131], v53, s[56:57] offset:64
	global_load_dwordx4 v[132:135], v53, s[56:57] offset:80
	global_load_dwordx4 v[136:139], v53, s[56:57] offset:96
	global_load_dwordx4 v[140:143], v53, s[56:57] offset:112
	global_load_dwordx4 v[144:147], v9, s[58:59] offset:-4
	global_load_dwordx4 v[148:151], v9, s[58:59] offset:12
	global_load_dwordx4 v[152:155], v9, s[58:59] offset:28
	global_load_dwordx4 v[156:159], v9, s[58:59] offset:44
	global_load_dwordx4 v[160:163], v9, s[58:59] offset:60
	global_load_dwordx4 v[164:167], v9, s[58:59] offset:76
	global_load_dwordx4 v[168:171], v9, s[58:59] offset:92
	global_load_dwordx4 v[172:175], v9, s[58:59] offset:108
	global_load_dword v178, v[2:3], off nt
	v_lshl_add_u64 v[2:3], v[2:3], 0, s[60:61]
	global_load_dword v179, v[2:3], off nt
	v_lshl_add_u64 v[2:3], v[2:3], 0, s[60:61]
	global_load_dword v180, v[2:3], off nt
	v_lshl_add_u64 v[2:3], v[2:3], 0, s[60:61]
	global_load_dword v181, v[2:3], off nt
	v_lshl_add_u64 v[2:3], v[2:3], 0, s[60:61]
	global_load_dword v182, v[2:3], off nt
	v_lshl_add_u64 v[2:3], v[2:3], 0, s[60:61]
	global_load_dword v183, v[2:3], off nt
	v_lshl_add_u64 v[2:3], v[2:3], 0, s[60:61]
	global_load_dword v184, v[2:3], off nt
	v_lshl_add_u64 v[2:3], v[2:3], 0, s[60:61]
	global_load_dword v185, v[2:3], off nt
	v_lshl_add_u64 v[2:3], v[2:3], 0, s[60:61]
	global_load_dword v186, v[2:3], off nt
	v_lshl_add_u64 v[2:3], v[2:3], 0, s[60:61]
	global_load_dword v187, v[2:3], off nt
	v_lshl_add_u64 v[2:3], v[2:3], 0, s[60:61]
	global_load_dword v188, v[2:3], off nt
	v_lshl_add_u64 v[2:3], v[2:3], 0, s[60:61]
	global_load_dword v189, v[2:3], off nt
	v_lshl_add_u64 v[2:3], v[2:3], 0, s[60:61]
	global_load_dword v190, v[2:3], off nt
	v_lshl_add_u64 v[2:3], v[2:3], 0, s[60:61]
	global_load_dword v191, v[2:3], off nt
	v_lshl_add_u64 v[2:3], v[2:3], 0, s[60:61]
	global_load_dword v192, v[2:3], off nt
	v_lshl_add_u64 v[2:3], v[2:3], 0, s[60:61]
	global_load_dword v193, v[2:3], off nt
	v_lshl_add_u64 v[2:3], v[2:3], 0, s[60:61]
	global_load_dword v194, v[2:3], off nt
	v_lshl_add_u64 v[2:3], v[2:3], 0, s[60:61]
	global_load_dword v195, v[2:3], off nt
	v_lshl_add_u64 v[2:3], v[2:3], 0, s[60:61]
	global_load_dword v196, v[2:3], off nt
	v_lshl_add_u64 v[2:3], v[2:3], 0, s[60:61]
	global_load_dword v197, v[2:3], off nt
	v_lshl_add_u64 v[2:3], v[2:3], 0, s[60:61]
	global_load_dword v198, v[2:3], off nt
	v_lshl_add_u64 v[2:3], v[2:3], 0, s[60:61]
	global_load_dword v199, v[2:3], off nt
	v_lshl_add_u64 v[2:3], v[2:3], 0, s[60:61]
	global_load_dword v200, v[2:3], off nt
	v_lshl_add_u64 v[2:3], v[2:3], 0, s[60:61]
	global_load_dword v201, v[2:3], off nt
	v_lshl_add_u64 v[2:3], v[2:3], 0, s[60:61]
	global_load_dword v202, v[2:3], off nt
	v_lshl_add_u64 v[2:3], v[2:3], 0, s[60:61]
	global_load_dword v203, v[2:3], off nt
	v_lshl_add_u64 v[2:3], v[2:3], 0, s[60:61]
	global_load_dword v204, v[2:3], off nt
	v_lshl_add_u64 v[2:3], v[2:3], 0, s[60:61]
	global_load_dword v205, v[2:3], off nt
	v_lshl_add_u64 v[2:3], v[2:3], 0, s[60:61]
	global_load_dword v206, v[2:3], off nt
	v_lshl_add_u64 v[2:3], v[2:3], 0, s[60:61]
	global_load_dword v207, v[2:3], off nt
	v_lshl_add_u64 v[2:3], v[2:3], 0, s[60:61]
	global_load_dword v208, v[2:3], off nt
	v_lshl_add_u64 v[2:3], v[2:3], 0, s[60:61]
	global_load_dword v209, v[2:3], off nt
	v_lshl_add_u64 v[2:3], v[2:3], 0, s[60:61]
	s_add_u32 s56, s56, 0x80
	s_addc_u32 s57, s57, 0
	s_add_u32 s58, s58, 0x80
	s_addc_u32 s59, s59, 0
	s_waitcnt vmcnt(31)
	v_mul_f32_e32 v210, 0xbfb8aa3b, v80
	v_mul_f32_e32 v211, 0xbfb8aa3b, v112
	v_mul_f32_e32 v212, 0xbfb8aa3b, v144
	v_exp_f32_e32 v210, v210
	v_exp_f32_e32 v211, v211
	v_exp_f32_e32 v212, v212
	v_add_f32_e32 v210, 1.0, v210
	v_add_f32_e32 v211, 1.0, v211
	v_add_f32_e32 v212, 1.0, v212
	v_rcp_f32_e32 v210, v210
	v_rcp_f32_e32 v211, v211
	v_rcp_f32_e32 v212, v212
	v_mul_f32_e32 v210, v80, v210
	v_mul_f32_e32 v211, v112, v211
	v_mul_f32_e32 v212, v144, v212
	v_fmac_f32_e32 v4, v178, v210
	v_fmac_f32_e32 v5, v178, v211
	v_fmac_f32_e32 v29, v178, v212
	s_waitcnt vmcnt(30)
; __device__ __forceinline__ float fsilu(float x) { return x * fsig(x); }
; __global__ void __launch_bounds__(512, 2) fwd_megakernel(Params Parg) {
;     ...
;                 r -= NCONV; const int kc = r / 144, nc = r % 144, n = nc * 64 + lane;
;                 float a0 = 0.f, a1 = 0.f, a2 = 0.f;
;                 for (int k = kc * 128; k < kc * 128 + 128; ++k) { const float w = __builtin_nontemporal_load(&w_mod[(size_t)k * (NMOD * D) + n]); a0 += fsilu(cvec[k]) * w; a1 += fsilu(cvec[D + k]) * w; a2 += fsilu(cctx[k]) * w; }
	v_mul_f32_e32 v210, 0xbfb8aa3b, v81
	v_mul_f32_e32 v211, 0xbfb8aa3b, v113
	v_mul_f32_e32 v212, 0xbfb8aa3b, v145
	v_exp_f32_e32 v210, v210
	v_exp_f32_e32 v211, v211
	v_exp_f32_e32 v212, v212
	v_add_f32_e32 v210, 1.0, v210
	v_add_f32_e32 v211, 1.0, v211
	v_add_f32_e32 v212, 1.0, v212
	v_rcp_f32_e32 v210, v210
	v_rcp_f32_e32 v211, v211
	v_rcp_f32_e32 v212, v212
	v_mul_f32_e32 v210, v81, v210
	v_mul_f32_e32 v211, v113, v211
	v_mul_f32_e32 v212, v145, v212
	v_fmac_f32_e32 v4, v179, v210
	v_fmac_f32_e32 v5, v179, v211
	v_fmac_f32_e32 v29, v179, v212
	s_waitcnt vmcnt(29)
	v_mul_f32_e32 v210, 0xbfb8aa3b, v82
	v_mul_f32_e32 v211, 0xbfb8aa3b, v114
	v_mul_f32_e32 v212, 0xbfb8aa3b, v146
	v_exp_f32_e32 v210, v210
	v_exp_f32_e32 v211, v211
	v_exp_f32_e32 v212, v212
	v_add_f32_e32 v210, 1.0, v210
	v_add_f32_e32 v211, 1.0, v211
	v_add_f32_e32 v212, 1.0, v212
	v_rcp_f32_e32 v210, v210
	v_rcp_f32_e32 v211, v211
	v_rcp_f32_e32 v212, v212
	v_mul_f32_e32 v210, v82, v210
	v_mul_f32_e32 v211, v114, v211
	v_mul_f32_e32 v212, v146, v212
	v_fmac_f32_e32 v4, v180, v210
	v_fmac_f32_e32 v5, v180, v211
	v_fmac_f32_e32 v29, v180, v212
	s_waitcnt vmcnt(28)
	v_mul_f32_e32 v210, 0xbfb8aa3b, v83
	v_mul_f32_e32 v211, 0xbfb8aa3b, v115
	v_mul_f32_e32 v212, 0xbfb8aa3b, v147
	v_exp_f32_e32 v210, v210
	v_exp_f32_e32 v211, v211
	v_exp_f32_e32 v212, v212
	v_add_f32_e32 v210, 1.0, v210
	v_add_f32_e32 v211, 1.0, v211
	v_add_f32_e32 v212, 1.0, v212
	v_rcp_f32_e32 v210, v210
	v_rcp_f32_e32 v211, v211
	v_rcp_f32_e32 v212, v212
	v_mul_f32_e32 v210, v83, v210
	v_mul_f32_e32 v211, v115, v211
	v_mul_f32_e32 v212, v147, v212
	v_fmac_f32_e32 v4, v181, v210
	v_fmac_f32_e32 v5, v181, v211
	v_fmac_f32_e32 v29, v181, v212
	s_waitcnt vmcnt(27)
	v_mul_f32_e32 v210, 0xbfb8aa3b, v84
	v_mul_f32_e32 v211, 0xbfb8aa3b, v116
	v_mul_f32_e32 v212, 0xbfb8aa3b, v148
	v_exp_f32_e32 v210, v210
	v_exp_f32_e32 v211, v211
	v_exp_f32_e32 v212, v212
	v_add_f32_e32 v210, 1.0, v210
	v_add_f32_e32 v211, 1.0, v211
	v_add_f32_e32 v212, 1.0, v212
	v_rcp_f32_e32 v210, v210
	v_rcp_f32_e32 v211, v211
	v_rcp_f32_e32 v212, v212
	v_mul_f32_e32 v210, v84, v210
	v_mul_f32_e32 v211, v116, v211
	v_mul_f32_e32 v212, v148, v212
	v_fmac_f32_e32 v4, v182, v210
	v_fmac_f32_e32 v5, v182, v211
	v_fmac_f32_e32 v29, v182, v212
	s_waitcnt vmcnt(26)
	v_mul_f32_e32 v210, 0xbfb8aa3b, v85
	v_mul_f32_e32 v211, 0xbfb8aa3b, v117
	v_mul_f32_e32 v212, 0xbfb8aa3b, v149
	v_exp_f32_e32 v210, v210
	v_exp_f32_e32 v211, v211
	v_exp_f32_e32 v212, v212
	v_add_f32_e32 v210, 1.0, v210
	v_add_f32_e32 v211, 1.0, v211
	v_add_f32_e32 v212, 1.0, v212
	v_rcp_f32_e32 v210, v210
	v_rcp_f32_e32 v211, v211
	v_rcp_f32_e32 v212, v212
	v_mul_f32_e32 v210, v85, v210
	v_mul_f32_e32 v211, v117, v211
	v_mul_f32_e32 v212, v149, v212
	v_fmac_f32_e32 v4, v183, v210
	v_fmac_f32_e32 v5, v183, v211
	v_fmac_f32_e32 v29, v183, v212
	s_waitcnt vmcnt(25)
	v_mul_f32_e32 v210, 0xbfb8aa3b, v86
	v_mul_f32_e32 v211, 0xbfb8aa3b, v118
	v_mul_f32_e32 v212, 0xbfb8aa3b, v150
	v_exp_f32_e32 v210, v210
	v_exp_f32_e32 v211, v211
	v_exp_f32_e32 v212, v212
	v_add_f32_e32 v210, 1.0, v210
	v_add_f32_e32 v211, 1.0, v211
	v_add_f32_e32 v212, 1.0, v212
	v_rcp_f32_e32 v210, v210
	v_rcp_f32_e32 v211, v211
	v_rcp_f32_e32 v212, v212
	v_mul_f32_e32 v210, v86, v210
	v_mul_f32_e32 v211, v118, v211
	v_mul_f32_e32 v212, v150, v212
	v_fmac_f32_e32 v4, v184, v210
	v_fmac_f32_e32 v5, v184, v211
	v_fmac_f32_e32 v29, v184, v212
	s_waitcnt vmcnt(24)
	v_mul_f32_e32 v210, 0xbfb8aa3b, v87
	v_mul_f32_e32 v211, 0xbfb8aa3b, v119
	v_mul_f32_e32 v212, 0xbfb8aa3b, v151
	v_exp_f32_e32 v210, v210
	v_exp_f32_e32 v211, v211
	v_exp_f32_e32 v212, v212
	v_add_f32_e32 v210, 1.0, v210
	v_add_f32_e32 v211, 1.0, v211
	v_add_f32_e32 v212, 1.0, v212
	v_rcp_f32_e32 v210, v210
	v_rcp_f32_e32 v211, v211
	v_rcp_f32_e32 v212, v212
	v_mul_f32_e32 v210, v87, v210
	v_mul_f32_e32 v211, v119, v211
	v_mul_f32_e32 v212, v151, v212
	v_fmac_f32_e32 v4, v185, v210
	v_fmac_f32_e32 v5, v185, v211
	v_fmac_f32_e32 v29, v185, v212
	s_waitcnt vmcnt(23)
	v_mul_f32_e32 v210, 0xbfb8aa3b, v88
	v_mul_f32_e32 v211, 0xbfb8aa3b, v120
	v_mul_f32_e32 v212, 0xbfb8aa3b, v152
	v_exp_f32_e32 v210, v210
	v_exp_f32_e32 v211, v211
	v_exp_f32_e32 v212, v212
	v_add_f32_e32 v210, 1.0, v210
	v_add_f32_e32 v211, 1.0, v211
	v_add_f32_e32 v212, 1.0, v212
	v_rcp_f32_e32 v210, v210
	v_rcp_f32_e32 v211, v211
	v_rcp_f32_e32 v212, v212
	v_mul_f32_e32 v210, v88, v210
	v_mul_f32_e32 v211, v120, v211
	v_mul_f32_e32 v212, v152, v212
	v_fmac_f32_e32 v4, v186, v210
	v_fmac_f32_e32 v5, v186, v211
	v_fmac_f32_e32 v29, v186, v212
	s_waitcnt vmcnt(22)
	v_mul_f32_e32 v210, 0xbfb8aa3b, v89
	v_mul_f32_e32 v211, 0xbfb8aa3b, v121
	v_mul_f32_e32 v212, 0xbfb8aa3b, v153
	v_exp_f32_e32 v210, v210
	v_exp_f32_e32 v211, v211
	v_exp_f32_e32 v212, v212
	v_add_f32_e32 v210, 1.0, v210
	v_add_f32_e32 v211, 1.0, v211
	v_add_f32_e32 v212, 1.0, v212
	v_rcp_f32_e32 v210, v210
	v_rcp_f32_e32 v211, v211
	v_rcp_f32_e32 v212, v212
	v_mul_f32_e32 v210, v89, v210
	v_mul_f32_e32 v211, v121, v211
	v_mul_f32_e32 v212, v153, v212
	v_fmac_f32_e32 v4, v187, v210
	v_fmac_f32_e32 v5, v187, v211
	v_fmac_f32_e32 v29, v187, v212
	s_waitcnt vmcnt(21)
	v_mul_f32_e32 v210, 0xbfb8aa3b, v90
	v_mul_f32_e32 v211, 0xbfb8aa3b, v122
	v_mul_f32_e32 v212, 0xbfb8aa3b, v154
	v_exp_f32_e32 v210, v210
	v_exp_f32_e32 v211, v211
	v_exp_f32_e32 v212, v212
	v_add_f32_e32 v210, 1.0, v210
	v_add_f32_e32 v211, 1.0, v211
	v_add_f32_e32 v212, 1.0, v212
	v_rcp_f32_e32 v210, v210
	v_rcp_f32_e32 v211, v211
	v_rcp_f32_e32 v212, v212
	v_mul_f32_e32 v210, v90, v210
	v_mul_f32_e32 v211, v122, v211
	v_mul_f32_e32 v212, v154, v212
	v_fmac_f32_e32 v4, v188, v210
	v_fmac_f32_e32 v5, v188, v211
	v_fmac_f32_e32 v29, v188, v212
	s_waitcnt vmcnt(20)
; __device__ __forceinline__ float fsilu(float x) { return x * fsig(x); }
; __global__ void __launch_bounds__(512, 2) fwd_megakernel(Params Parg) {
;     ...
;                 r -= NCONV; const int kc = r / 144, nc = r % 144, n = nc * 64 + lane;
;                 float a0 = 0.f, a1 = 0.f, a2 = 0.f;
;                 for (int k = kc * 128; k < kc * 128 + 128; ++k) { const float w = __builtin_nontemporal_load(&w_mod[(size_t)k * (NMOD * D) + n]); a0 += fsilu(cvec[k]) * w; a1 += fsilu(cvec[D + k]) * w; a2 += fsilu(cctx[k]) * w; }
	v_mul_f32_e32 v210, 0xbfb8aa3b, v91
	v_mul_f32_e32 v211, 0xbfb8aa3b, v123
	v_mul_f32_e32 v212, 0xbfb8aa3b, v155
	v_exp_f32_e32 v210, v210
	v_exp_f32_e32 v211, v211
	v_exp_f32_e32 v212, v212
	v_add_f32_e32 v210, 1.0, v210
	v_add_f32_e32 v211, 1.0, v211
	v_add_f32_e32 v212, 1.0, v212
	v_rcp_f32_e32 v210, v210
	v_rcp_f32_e32 v211, v211
	v_rcp_f32_e32 v212, v212
	v_mul_f32_e32 v210, v91, v210
	v_mul_f32_e32 v211, v123, v211
	v_mul_f32_e32 v212, v155, v212
	v_fmac_f32_e32 v4, v189, v210
	v_fmac_f32_e32 v5, v189, v211
	v_fmac_f32_e32 v29, v189, v212
	s_waitcnt vmcnt(19)
	v_mul_f32_e32 v210, 0xbfb8aa3b, v92
	v_mul_f32_e32 v211, 0xbfb8aa3b, v124
	v_mul_f32_e32 v212, 0xbfb8aa3b, v156
	v_exp_f32_e32 v210, v210
	v_exp_f32_e32 v211, v211
	v_exp_f32_e32 v212, v212
	v_add_f32_e32 v210, 1.0, v210
	v_add_f32_e32 v211, 1.0, v211
	v_add_f32_e32 v212, 1.0, v212
	v_rcp_f32_e32 v210, v210
	v_rcp_f32_e32 v211, v211
	v_rcp_f32_e32 v212, v212
	v_mul_f32_e32 v210, v92, v210
	v_mul_f32_e32 v211, v124, v211
	v_mul_f32_e32 v212, v156, v212
	v_fmac_f32_e32 v4, v190, v210
	v_fmac_f32_e32 v5, v190, v211
	v_fmac_f32_e32 v29, v190, v212
	s_waitcnt vmcnt(18)
	v_mul_f32_e32 v210, 0xbfb8aa3b, v93
	v_mul_f32_e32 v211, 0xbfb8aa3b, v125
	v_mul_f32_e32 v212, 0xbfb8aa3b, v157
	v_exp_f32_e32 v210, v210
	v_exp_f32_e32 v211, v211
	v_exp_f32_e32 v212, v212
	v_add_f32_e32 v210, 1.0, v210
	v_add_f32_e32 v211, 1.0, v211
	v_add_f32_e32 v212, 1.0, v212
	v_rcp_f32_e32 v210, v210
	v_rcp_f32_e32 v211, v211
	v_rcp_f32_e32 v212, v212
	v_mul_f32_e32 v210, v93, v210
	v_mul_f32_e32 v211, v125, v211
	v_mul_f32_e32 v212, v157, v212
	v_fmac_f32_e32 v4, v191, v210
	v_fmac_f32_e32 v5, v191, v211
	v_fmac_f32_e32 v29, v191, v212
	s_waitcnt vmcnt(17)
	v_mul_f32_e32 v210, 0xbfb8aa3b, v94
	v_mul_f32_e32 v211, 0xbfb8aa3b, v126
	v_mul_f32_e32 v212, 0xbfb8aa3b, v158
	v_exp_f32_e32 v210, v210
	v_exp_f32_e32 v211, v211
	v_exp_f32_e32 v212, v212
	v_add_f32_e32 v210, 1.0, v210
	v_add_f32_e32 v211, 1.0, v211
	v_add_f32_e32 v212, 1.0, v212
	v_rcp_f32_e32 v210, v210
	v_rcp_f32_e32 v211, v211
	v_rcp_f32_e32 v212, v212
	v_mul_f32_e32 v210, v94, v210
	v_mul_f32_e32 v211, v126, v211
	v_mul_f32_e32 v212, v158, v212
	v_fmac_f32_e32 v4, v192, v210
	v_fmac_f32_e32 v5, v192, v211
	v_fmac_f32_e32 v29, v192, v212
	s_waitcnt vmcnt(16)
	v_mul_f32_e32 v210, 0xbfb8aa3b, v95
	v_mul_f32_e32 v211, 0xbfb8aa3b, v127
	v_mul_f32_e32 v212, 0xbfb8aa3b, v159
	v_exp_f32_e32 v210, v210
	v_exp_f32_e32 v211, v211
	v_exp_f32_e32 v212, v212
	v_add_f32_e32 v210, 1.0, v210
	v_add_f32_e32 v211, 1.0, v211
	v_add_f32_e32 v212, 1.0, v212
	v_rcp_f32_e32 v210, v210
	v_rcp_f32_e32 v211, v211
	v_rcp_f32_e32 v212, v212
	v_mul_f32_e32 v210, v95, v210
	v_mul_f32_e32 v211, v127, v211
	v_mul_f32_e32 v212, v159, v212
	v_fmac_f32_e32 v4, v193, v210
	v_fmac_f32_e32 v5, v193, v211
	v_fmac_f32_e32 v29, v193, v212
	s_waitcnt vmcnt(15)
	v_mul_f32_e32 v210, 0xbfb8aa3b, v96
	v_mul_f32_e32 v211, 0xbfb8aa3b, v128
	v_mul_f32_e32 v212, 0xbfb8aa3b, v160
	v_exp_f32_e32 v210, v210
	v_exp_f32_e32 v211, v211
	v_exp_f32_e32 v212, v212
	v_add_f32_e32 v210, 1.0, v210
	v_add_f32_e32 v211, 1.0, v211
	v_add_f32_e32 v212, 1.0, v212
	v_rcp_f32_e32 v210, v210
	v_rcp_f32_e32 v211, v211
	v_rcp_f32_e32 v212, v212
	v_mul_f32_e32 v210, v96, v210
	v_mul_f32_e32 v211, v128, v211
	v_mul_f32_e32 v212, v160, v212
	v_fmac_f32_e32 v4, v194, v210
	v_fmac_f32_e32 v5, v194, v211
	v_fmac_f32_e32 v29, v194, v212
	s_waitcnt vmcnt(14)
	v_mul_f32_e32 v210, 0xbfb8aa3b, v97
	v_mul_f32_e32 v211, 0xbfb8aa3b, v129
	v_mul_f32_e32 v212, 0xbfb8aa3b, v161
	v_exp_f32_e32 v210, v210
	v_exp_f32_e32 v211, v211
	v_exp_f32_e32 v212, v212
	v_add_f32_e32 v210, 1.0, v210
	v_add_f32_e32 v211, 1.0, v211
	v_add_f32_e32 v212, 1.0, v212
	v_rcp_f32_e32 v210, v210
	v_rcp_f32_e32 v211, v211
	v_rcp_f32_e32 v212, v212
	v_mul_f32_e32 v210, v97, v210
	v_mul_f32_e32 v211, v129, v211
	v_mul_f32_e32 v212, v161, v212
	v_fmac_f32_e32 v4, v195, v210
	v_fmac_f32_e32 v5, v195, v211
	v_fmac_f32_e32 v29, v195, v212
	s_waitcnt vmcnt(13)
	v_mul_f32_e32 v210, 0xbfb8aa3b, v98
	v_mul_f32_e32 v211, 0xbfb8aa3b, v130
	v_mul_f32_e32 v212, 0xbfb8aa3b, v162
	v_exp_f32_e32 v210, v210
	v_exp_f32_e32 v211, v211
	v_exp_f32_e32 v212, v212
	v_add_f32_e32 v210, 1.0, v210
	v_add_f32_e32 v211, 1.0, v211
	v_add_f32_e32 v212, 1.0, v212
	v_rcp_f32_e32 v210, v210
	v_rcp_f32_e32 v211, v211
	v_rcp_f32_e32 v212, v212
	v_mul_f32_e32 v210, v98, v210
	v_mul_f32_e32 v211, v130, v211
	v_mul_f32_e32 v212, v162, v212
	v_fmac_f32_e32 v4, v196, v210
	v_fmac_f32_e32 v5, v196, v211
	v_fmac_f32_e32 v29, v196, v212
	s_waitcnt vmcnt(12)
	v_mul_f32_e32 v210, 0xbfb8aa3b, v99
	v_mul_f32_e32 v211, 0xbfb8aa3b, v131
	v_mul_f32_e32 v212, 0xbfb8aa3b, v163
	v_exp_f32_e32 v210, v210
	v_exp_f32_e32 v211, v211
	v_exp_f32_e32 v212, v212
	v_add_f32_e32 v210, 1.0, v210
	v_add_f32_e32 v211, 1.0, v211
	v_add_f32_e32 v212, 1.0, v212
	v_rcp_f32_e32 v210, v210
	v_rcp_f32_e32 v211, v211
	v_rcp_f32_e32 v212, v212
	v_mul_f32_e32 v210, v99, v210
	v_mul_f32_e32 v211, v131, v211
	v_mul_f32_e32 v212, v163, v212
	v_fmac_f32_e32 v4, v197, v210
	v_fmac_f32_e32 v5, v197, v211
	v_fmac_f32_e32 v29, v197, v212
	s_waitcnt vmcnt(11)
	v_mul_f32_e32 v210, 0xbfb8aa3b, v100
	v_mul_f32_e32 v211, 0xbfb8aa3b, v132
	v_mul_f32_e32 v212, 0xbfb8aa3b, v164
	v_exp_f32_e32 v210, v210
	v_exp_f32_e32 v211, v211
	v_exp_f32_e32 v212, v212
	v_add_f32_e32 v210, 1.0, v210
	v_add_f32_e32 v211, 1.0, v211
	v_add_f32_e32 v212, 1.0, v212
	v_rcp_f32_e32 v210, v210
	v_rcp_f32_e32 v211, v211
	v_rcp_f32_e32 v212, v212
	v_mul_f32_e32 v210, v100, v210
	v_mul_f32_e32 v211, v132, v211
	v_mul_f32_e32 v212, v164, v212
	v_fmac_f32_e32 v4, v198, v210
	v_fmac_f32_e32 v5, v198, v211
	v_fmac_f32_e32 v29, v198, v212
	s_waitcnt vmcnt(10)
; __device__ __forceinline__ float fsilu(float x) { return x * fsig(x); }
; __global__ void __launch_bounds__(512, 2) fwd_megakernel(Params Parg) {
;     ...
;                 r -= NCONV; const int kc = r / 144, nc = r % 144, n = nc * 64 + lane;
;                 float a0 = 0.f, a1 = 0.f, a2 = 0.f;
;                 for (int k = kc * 128; k < kc * 128 + 128; ++k) { const float w = __builtin_nontemporal_load(&w_mod[(size_t)k * (NMOD * D) + n]); a0 += fsilu(cvec[k]) * w; a1 += fsilu(cvec[D + k]) * w; a2 += fsilu(cctx[k]) * w; }
;                 part[(kc * 3 + 0) * (NMOD * D) + n] = a0; part[(kc * 3 + 1) * (NMOD * D) + n] = a1; part[(kc * 3 + 2) * (NMOD * D) + n] = a2;
	v_mul_f32_e32 v210, 0xbfb8aa3b, v101
	v_mul_f32_e32 v211, 0xbfb8aa3b, v133
	v_mul_f32_e32 v212, 0xbfb8aa3b, v165
	v_exp_f32_e32 v210, v210
	v_exp_f32_e32 v211, v211
	v_exp_f32_e32 v212, v212
	v_add_f32_e32 v210, 1.0, v210
	v_add_f32_e32 v211, 1.0, v211
	v_add_f32_e32 v212, 1.0, v212
	v_rcp_f32_e32 v210, v210
	v_rcp_f32_e32 v211, v211
	v_rcp_f32_e32 v212, v212
	v_mul_f32_e32 v210, v101, v210
	v_mul_f32_e32 v211, v133, v211
	v_mul_f32_e32 v212, v165, v212
	v_fmac_f32_e32 v4, v199, v210
	v_fmac_f32_e32 v5, v199, v211
	v_fmac_f32_e32 v29, v199, v212
	s_waitcnt vmcnt(9)
	v_mul_f32_e32 v210, 0xbfb8aa3b, v102
	v_mul_f32_e32 v211, 0xbfb8aa3b, v134
	v_mul_f32_e32 v212, 0xbfb8aa3b, v166
	v_exp_f32_e32 v210, v210
	v_exp_f32_e32 v211, v211
	v_exp_f32_e32 v212, v212
	v_add_f32_e32 v210, 1.0, v210
	v_add_f32_e32 v211, 1.0, v211
	v_add_f32_e32 v212, 1.0, v212
	v_rcp_f32_e32 v210, v210
	v_rcp_f32_e32 v211, v211
	v_rcp_f32_e32 v212, v212
	v_mul_f32_e32 v210, v102, v210
	v_mul_f32_e32 v211, v134, v211
	v_mul_f32_e32 v212, v166, v212
	v_fmac_f32_e32 v4, v200, v210
	v_fmac_f32_e32 v5, v200, v211
	v_fmac_f32_e32 v29, v200, v212
	s_waitcnt vmcnt(8)
	v_mul_f32_e32 v210, 0xbfb8aa3b, v103
	v_mul_f32_e32 v211, 0xbfb8aa3b, v135
	v_mul_f32_e32 v212, 0xbfb8aa3b, v167
	v_exp_f32_e32 v210, v210
	v_exp_f32_e32 v211, v211
	v_exp_f32_e32 v212, v212
	v_add_f32_e32 v210, 1.0, v210
	v_add_f32_e32 v211, 1.0, v211
	v_add_f32_e32 v212, 1.0, v212
	v_rcp_f32_e32 v210, v210
	v_rcp_f32_e32 v211, v211
	v_rcp_f32_e32 v212, v212
	v_mul_f32_e32 v210, v103, v210
	v_mul_f32_e32 v211, v135, v211
	v_mul_f32_e32 v212, v167, v212
	v_fmac_f32_e32 v4, v201, v210
	v_fmac_f32_e32 v5, v201, v211
	v_fmac_f32_e32 v29, v201, v212
	s_waitcnt vmcnt(7)
	v_mul_f32_e32 v210, 0xbfb8aa3b, v104
	v_mul_f32_e32 v211, 0xbfb8aa3b, v136
	v_mul_f32_e32 v212, 0xbfb8aa3b, v168
	v_exp_f32_e32 v210, v210
	v_exp_f32_e32 v211, v211
	v_exp_f32_e32 v212, v212
	v_add_f32_e32 v210, 1.0, v210
	v_add_f32_e32 v211, 1.0, v211
	v_add_f32_e32 v212, 1.0, v212
	v_rcp_f32_e32 v210, v210
	v_rcp_f32_e32 v211, v211
	v_rcp_f32_e32 v212, v212
	v_mul_f32_e32 v210, v104, v210
	v_mul_f32_e32 v211, v136, v211
	v_mul_f32_e32 v212, v168, v212
	v_fmac_f32_e32 v4, v202, v210
	v_fmac_f32_e32 v5, v202, v211
	v_fmac_f32_e32 v29, v202, v212
	s_waitcnt vmcnt(6)
	v_mul_f32_e32 v210, 0xbfb8aa3b, v105
	v_mul_f32_e32 v211, 0xbfb8aa3b, v137
	v_mul_f32_e32 v212, 0xbfb8aa3b, v169
	v_exp_f32_e32 v210, v210
	v_exp_f32_e32 v211, v211
	v_exp_f32_e32 v212, v212
	v_add_f32_e32 v210, 1.0, v210
	v_add_f32_e32 v211, 1.0, v211
	v_add_f32_e32 v212, 1.0, v212
	v_rcp_f32_e32 v210, v210
	v_rcp_f32_e32 v211, v211
	v_rcp_f32_e32 v212, v212
	v_mul_f32_e32 v210, v105, v210
	v_mul_f32_e32 v211, v137, v211
	v_mul_f32_e32 v212, v169, v212
	v_fmac_f32_e32 v4, v203, v210
	v_fmac_f32_e32 v5, v203, v211
	v_fmac_f32_e32 v29, v203, v212
	s_waitcnt vmcnt(5)
	v_mul_f32_e32 v210, 0xbfb8aa3b, v106
	v_mul_f32_e32 v211, 0xbfb8aa3b, v138
	v_mul_f32_e32 v212, 0xbfb8aa3b, v170
	v_exp_f32_e32 v210, v210
	v_exp_f32_e32 v211, v211
	v_exp_f32_e32 v212, v212
	v_add_f32_e32 v210, 1.0, v210
	v_add_f32_e32 v211, 1.0, v211
	v_add_f32_e32 v212, 1.0, v212
	v_rcp_f32_e32 v210, v210
	v_rcp_f32_e32 v211, v211
	v_rcp_f32_e32 v212, v212
	v_mul_f32_e32 v210, v106, v210
	v_mul_f32_e32 v211, v138, v211
	v_mul_f32_e32 v212, v170, v212
	v_fmac_f32_e32 v4, v204, v210
	v_fmac_f32_e32 v5, v204, v211
	v_fmac_f32_e32 v29, v204, v212
	s_waitcnt vmcnt(4)
	v_mul_f32_e32 v210, 0xbfb8aa3b, v107
	v_mul_f32_e32 v211, 0xbfb8aa3b, v139
	v_mul_f32_e32 v212, 0xbfb8aa3b, v171
	v_exp_f32_e32 v210, v210
	v_exp_f32_e32 v211, v211
	v_exp_f32_e32 v212, v212
	v_add_f32_e32 v210, 1.0, v210
	v_add_f32_e32 v211, 1.0, v211
	v_add_f32_e32 v212, 1.0, v212
	v_rcp_f32_e32 v210, v210
	v_rcp_f32_e32 v211, v211
	v_rcp_f32_e32 v212, v212
	v_mul_f32_e32 v210, v107, v210
	v_mul_f32_e32 v211, v139, v211
	v_mul_f32_e32 v212, v171, v212
	v_fmac_f32_e32 v4, v205, v210
	v_fmac_f32_e32 v5, v205, v211
	v_fmac_f32_e32 v29, v205, v212
	s_waitcnt vmcnt(3)
	v_mul_f32_e32 v210, 0xbfb8aa3b, v108
	v_mul_f32_e32 v211, 0xbfb8aa3b, v140
	v_mul_f32_e32 v212, 0xbfb8aa3b, v172
	v_exp_f32_e32 v210, v210
	v_exp_f32_e32 v211, v211
	v_exp_f32_e32 v212, v212
	v_add_f32_e32 v210, 1.0, v210
	v_add_f32_e32 v211, 1.0, v211
	v_add_f32_e32 v212, 1.0, v212
	v_rcp_f32_e32 v210, v210
	v_rcp_f32_e32 v211, v211
	v_rcp_f32_e32 v212, v212
	v_mul_f32_e32 v210, v108, v210
	v_mul_f32_e32 v211, v140, v211
	v_mul_f32_e32 v212, v172, v212
	v_fmac_f32_e32 v4, v206, v210
	v_fmac_f32_e32 v5, v206, v211
	v_fmac_f32_e32 v29, v206, v212
	s_waitcnt vmcnt(2)
	v_mul_f32_e32 v210, 0xbfb8aa3b, v109
	v_mul_f32_e32 v211, 0xbfb8aa3b, v141
	v_mul_f32_e32 v212, 0xbfb8aa3b, v173
	v_exp_f32_e32 v210, v210
	v_exp_f32_e32 v211, v211
	v_exp_f32_e32 v212, v212
	v_add_f32_e32 v210, 1.0, v210
	v_add_f32_e32 v211, 1.0, v211
	v_add_f32_e32 v212, 1.0, v212
	v_rcp_f32_e32 v210, v210
	v_rcp_f32_e32 v211, v211
	v_rcp_f32_e32 v212, v212
	v_mul_f32_e32 v210, v109, v210
	v_mul_f32_e32 v211, v141, v211
	v_mul_f32_e32 v212, v173, v212
	v_fmac_f32_e32 v4, v207, v210
	v_fmac_f32_e32 v5, v207, v211
	v_fmac_f32_e32 v29, v207, v212
	s_waitcnt vmcnt(1)
	v_mul_f32_e32 v210, 0xbfb8aa3b, v110
	v_mul_f32_e32 v211, 0xbfb8aa3b, v142
	v_mul_f32_e32 v212, 0xbfb8aa3b, v174
	v_exp_f32_e32 v210, v210
	v_exp_f32_e32 v211, v211
	v_exp_f32_e32 v212, v212
	v_add_f32_e32 v210, 1.0, v210
	v_add_f32_e32 v211, 1.0, v211
	v_add_f32_e32 v212, 1.0, v212
	v_rcp_f32_e32 v210, v210
	v_rcp_f32_e32 v211, v211
	v_rcp_f32_e32 v212, v212
	v_mul_f32_e32 v210, v110, v210
	v_mul_f32_e32 v211, v142, v211
	v_mul_f32_e32 v212, v174, v212
	v_fmac_f32_e32 v4, v208, v210
	v_fmac_f32_e32 v5, v208, v211
	v_fmac_f32_e32 v29, v208, v212
	s_waitcnt vmcnt(0)
	v_mul_f32_e32 v210, 0xbfb8aa3b, v111
	v_mul_f32_e32 v211, 0xbfb8aa3b, v143
	v_mul_f32_e32 v212, 0xbfb8aa3b, v175
	v_exp_f32_e32 v210, v210
	v_exp_f32_e32 v211, v211
	v_exp_f32_e32 v212, v212
	v_add_f32_e32 v210, 1.0, v210
	v_add_f32_e32 v211, 1.0, v211
	v_add_f32_e32 v212, 1.0, v212
	v_rcp_f32_e32 v210, v210
	v_rcp_f32_e32 v211, v211
	v_rcp_f32_e32 v212, v212
	v_mul_f32_e32 v210, v111, v210
	v_mul_f32_e32 v211, v143, v211
	v_mul_f32_e32 v212, v175, v212
	v_fmac_f32_e32 v4, v209, v210
	v_fmac_f32_e32 v5, v209, v211
	v_fmac_f32_e32 v29, v209, v212
	s_add_i32 s62, s62, -1
	s_cmp_lg_u32 s62, 0
	s_cbranch_scc1 .Lmods_batch
	s_mulk_i32 s24, 0x6c00
	v_add_lshl_u32 v8, v28, s24, 2
	v_lshl_add_u64 v[2:3], s[22:23], 0, v[8:9]
	v_add_co_u32_e32 v30, vcc, 0x9000, v2
	global_store_dword v8, v4, s[22:23]
	s_nop 0
	v_addc_co_u32_e32 v31, vcc, 0, v3, vcc
	v_add_co_u32_e32 v2, vcc, 0x12000, v2
	global_store_dword v[30:31], v5, off
	s_nop 0
	v_addc_co_u32_e32 v3, vcc, 0, v3, vcc
	global_store_dword v[2:3], v29, off
	s_branch .LBB0_7
